# peeled first K-iteration of the in-proj and gate-int8 loops: L1/L2 waits no longer force the previous epilogue's stores to drain; phase prologues drain fully
# speedup vs baseline: 1.0045x; 1.0045x over previous
.LBB0_284:
	v_readlane_b32 s4, v249, 63
	v_readlane_b32 s5, v248, 0
	s_andn2_b64 vcc, exec, s[4:5]
	s_cbranch_vccnz .LBB0_420
	v_bfe_i32 v5, v2, 27, 1
	v_lshlrev_b32_e32 v3, 4, v2
	v_lshrrev_b32_e32 v5, 22, v5
	v_add_u32_e32 v5, v3, v5
	v_and_b32_e32 v5, 0xfffffc00, v5
	v_ashrrev_i32_e32 v4, 31, v2
	v_sub_u32_e32 v3, v3, v5
	v_lshrrev_b32_e32 v4, 26, v4
	v_lshrrev_b32_e32 v5, 4, v3
	v_add_u32_e32 v4, v2, v4
	v_bitop3_b32 v5, v5, v3, 32 bitop3:0x6c
	v_ashrrev_i32_e32 v3, 31, v3
	v_ashrrev_i32_e32 v4, 6, v4
	v_lshrrev_b32_e32 v3, 26, v3
	v_lshlrev_b32_e32 v6, 3, v4
	v_add_u32_e32 v3, v5, v3
	v_and_b32_e32 v6, -16, v6
	v_ashrrev_i32_e32 v3, 6, v3
	v_add_u32_e32 v6, v3, v6
	v_mul_i32_i24_e32 v7, 64, v3
	v_sub_u32_e32 v5, v5, v7
	v_lshrrev_b32_e32 v8, 2, v6
	s_ashr_i32 s17, s16, 6
	v_lshlrev_b32_e32 v4, 5, v4
	v_ashrrev_i16_sdwa v5, v229, sext(v5) dst_sel:DWORD dst_unused:UNUSED_PAD src0_sel:DWORD src1_sel:BYTE_0
	v_lshlrev_b32_e32 v7, 1, v6
	v_and_b32_e32 v8, 4, v8
	v_and_b32_e32 v4, 32, v4
	v_bfe_i32 v5, v5, 0, 16
	v_and_b32_e32 v7, 24, v7
	v_and_or_b32 v3, v3, 3, v8
	s_lshl_b32 s45, s17, 10
	v_and_b32_e32 v8, 0xfffe0, v6
	v_or3_b32 v3, v7, v3, v8
	v_add_lshl_u32 v4, v4, v5, 1
	s_mov_b64 s[4:5], s[38:39]
	s_add_i32 s46, s45, 0
	s_ashr_i32 s18, s16, 8
	v_lshl_add_u32 v202, v3, 12, v4
	s_add_i32 m0, s46, 0x10000
	v_lshl_add_u32 v208, v6, 12, v4
	global_load_lds_dwordx4 v202, s[4:5]
	s_add_u32 s4, s4, 0x40000
	s_addc_u32 s5, s5, 0
	s_add_i32 m0, s46, 0x12000
	s_nop 0
	global_load_lds_dwordx4 v202, s[4:5]
	s_add_u32 s4, s38, 0x80000
	s_addc_u32 s5, s39, 0
	s_add_i32 m0, s46, 0x14000
	s_nop 0
	global_load_lds_dwordx4 v202, s[4:5]
	s_add_u32 s4, s4, 0x40000
	s_addc_u32 s5, s5, 0
	s_add_i32 m0, s46, 0x16000
	s_nop 0
	global_load_lds_dwordx4 v202, s[4:5]
	s_mov_b64 s[4:5], s[40:41]
	s_mov_b32 m0, s46
	s_nop 0
	global_load_lds_dwordx4 v208, s[4:5]
	s_add_u32 s4, s4, 0x40000
	s_addc_u32 s5, s5, 0
	s_add_i32 s47, s46, 0x2000
	s_mov_b32 m0, s47
	s_nop 0
	global_load_lds_dwordx4 v208, s[4:5]
	s_add_u32 s4, s40, 0x80000
	s_addc_u32 s5, s41, 0
	s_add_i32 s48, s46, 0x4000
	s_mov_b32 m0, s48
	s_nop 0
	global_load_lds_dwordx4 v208, s[4:5]
	s_add_u32 s4, s4, 0x40000
	s_addc_u32 s5, s5, 0
	s_add_i32 s49, s46, 0x6000
	s_mov_b32 m0, s49
	s_nop 0
	global_load_lds_dwordx4 v208, s[4:5]
	s_add_u32 s4, s38, 0x80
	s_addc_u32 s5, s39, 0
	s_add_i32 m0, s46, 0x18000
	s_nop 0
	global_load_lds_dwordx4 v202, s[4:5]
	s_add_u32 s4, s4, 0x40000
	s_addc_u32 s5, s5, 0
	s_add_i32 m0, s46, 0x1a000
	s_nop 0
	global_load_lds_dwordx4 v202, s[4:5]
	s_add_u32 s4, s40, 0x80
	s_addc_u32 s5, s41, 0
	s_add_i32 s50, s46, 0x8000
	s_mov_b32 m0, s50
	s_nop 0
	global_load_lds_dwordx4 v208, s[4:5]
	s_add_u32 s4, s4, 0x40000
	s_addc_u32 s5, s5, 0
	s_add_i32 s51, s46, 0xa000
	s_mov_b32 m0, s51
	s_nop 0
	global_load_lds_dwordx4 v208, s[4:5]
	s_add_u32 s4, s38, 0x80080
	s_addc_u32 s5, s39, 0
	s_add_i32 m0, s46, 0x1c000
	s_nop 0
	global_load_lds_dwordx4 v202, s[4:5]
	s_add_u32 s4, s4, 0x40000
	s_addc_u32 s5, s5, 0
	s_add_i32 m0, s46, 0x1e000
	s_cmp_eq_u32 s18, 1
	global_load_lds_dwordx4 v202, s[4:5]
	s_waitcnt vmcnt(0)
	s_cselect_b64 s[4:5], -1, 0
	s_cmp_lg_u32 s18, 1
	s_cbranch_scc1 .LBB0_287
	s_barrier

.LBB0_292:
	s_add_u32 s19, s40, 0x100
	s_addc_u32 s54, s41, 0
	s_add_u32 s55, s38, 0x100
	v_mov_b32_e32 v2, 0
	s_addc_u32 s56, s39, 0
	s_mov_b32 s57, -2
	v_mov_b32_e32 v3, v2
	v_mov_b32_e32 v4, v2
	v_mov_b32_e32 v5, v2
	v_mov_b32_e32 v6, v2
	v_mov_b32_e32 v7, v2
	v_mov_b32_e32 v8, v2
	v_mov_b32_e32 v9, v2
	s_waitcnt vmcnt(8)
	s_cmp_eq_u32 s57, 28
	s_cselect_b32 s42, s10, s19
	s_cselect_b32 s43, s11, s54
	s_cselect_b32 s40, s26, s55
	s_cselect_b32 s41, s27, s56
	s_add_u32 s38, s42, 0x80
	s_addc_u32 s39, s43, 0
	s_add_i32 s60, 0, 0x10000
	s_add_i32 s61, 0, 0x14000
	v_add_u32_e32 v70, s60, v207
	v_add_u32_e32 v110, s61, v207
	ds_read_b128 v[42:45], v70
	ds_read_b128 v[46:49], v70 offset:1024
	ds_read_b128 v[66:69], v70 offset:2048
	ds_read_b128 v[70:73], v70 offset:3072
	ds_read_b128 v[86:89], v110
	ds_read_b128 v[90:93], v110 offset:1024
	ds_read_b128 v[106:109], v110 offset:2048
	ds_read_b128 v[110:113], v110 offset:3072
	s_add_u32 s58, s19, 0x7ff80
	s_addc_u32 s59, s54, 0
	ds_read_b128 v[130:133], v237
	ds_read_b128 v[134:137], v237 offset:1024
	ds_read_b128 v[154:157], v237 offset:2048
	ds_read_b128 v[158:161], v237 offset:3072
	ds_read_b128 v[178:181], v237 offset:4096
	ds_read_b128 v[182:185], v237 offset:5120
	ds_read_b128 v[186:189], v237 offset:6144
	ds_read_b128 v[190:193], v237 offset:7168
	s_add_i32 m0, s46, 0xc000
	v_lshl_add_u64 v[194:195], s[58:59], 0, v[208:209]
	s_add_u32 s58, s58, 0x40000
	s_addc_u32 s59, s59, 0
	global_load_lds_dwordx4 v[194:195], off
	s_add_i32 m0, s46, 0xe000
	v_lshl_add_u64 v[194:195], s[58:59], 0, v[208:209]
	global_load_lds_dwordx4 v[194:195], off
	s_waitcnt vmcnt(10)
	s_waitcnt lgkmcnt(0)
	s_barrier
	v_mfma_f32_16x16x32_bf16 v[174:177], v[42:45], v[130:133], 0
	v_mfma_f32_16x16x32_bf16 v[170:173], v[66:69], v[130:133], 0
	v_mfma_f32_16x16x32_bf16 v[150:153], v[42:45], v[154:157], 0
	v_mfma_f32_16x16x32_bf16 v[146:149], v[66:69], v[154:157], 0
	v_mfma_f32_16x16x32_bf16 v[126:129], v[42:45], v[178:181], 0
	v_mfma_f32_16x16x32_bf16 v[122:125], v[66:69], v[178:181], 0
	v_mfma_f32_16x16x32_bf16 v[102:105], v[42:45], v[186:189], 0
	v_mfma_f32_16x16x32_bf16 v[98:101], v[66:69], v[186:189], 0
	v_mfma_f32_16x16x32_bf16 v[174:177], v[46:49], v[134:137], v[174:177]
	v_mfma_f32_16x16x32_bf16 v[170:173], v[70:73], v[134:137], v[170:173]
	v_mfma_f32_16x16x32_bf16 v[150:153], v[46:49], v[158:161], v[150:153]
	v_mfma_f32_16x16x32_bf16 v[146:149], v[70:73], v[158:161], v[146:149]
	v_mfma_f32_16x16x32_bf16 v[126:129], v[46:49], v[182:185], v[126:129]
	v_mfma_f32_16x16x32_bf16 v[122:125], v[70:73], v[182:185], v[122:125]
	v_mfma_f32_16x16x32_bf16 v[102:105], v[46:49], v[190:193], v[102:105]
	v_mfma_f32_16x16x32_bf16 v[98:101], v[70:73], v[190:193], v[98:101]
	v_mfma_f32_16x16x32_bf16 v[166:169], v[86:89], v[130:133], 0
	v_mfma_f32_16x16x32_bf16 v[130:133], v[106:109], v[130:133], 0
	v_mfma_f32_16x16x32_bf16 v[138:141], v[106:109], v[154:157], 0
	v_mfma_f32_16x16x32_bf16 v[118:121], v[86:89], v[178:181], 0
	v_mfma_f32_16x16x32_bf16 v[114:117], v[106:109], v[178:181], 0
	v_mfma_f32_16x16x32_bf16 v[94:97], v[86:89], v[186:189], 0
	v_mfma_f32_16x16x32_bf16 v[82:85], v[106:109], v[186:189], 0
	v_mfma_f32_16x16x32_bf16 v[166:169], v[90:93], v[134:137], v[166:169]
	v_mfma_f32_16x16x32_bf16 v[130:133], v[110:113], v[134:137], v[130:133]
	v_mfma_f32_16x16x32_bf16 v[134:137], v[86:89], v[154:157], 0
	v_mfma_f32_16x16x32_bf16 v[138:141], v[110:113], v[158:161], v[138:141]
	v_mfma_f32_16x16x32_bf16 v[118:121], v[90:93], v[182:185], v[118:121]
	v_mfma_f32_16x16x32_bf16 v[114:117], v[110:113], v[182:185], v[114:117]
	v_mfma_f32_16x16x32_bf16 v[94:97], v[90:93], v[190:193], v[94:97]
	v_mfma_f32_16x16x32_bf16 v[82:85], v[110:113], v[190:193], v[82:85]
	v_mfma_f32_16x16x32_bf16 v[134:137], v[90:93], v[158:161], v[134:137]
	s_barrier
	s_mov_b64 s[58:59], s[40:41]
	ds_read_b128 v[142:145], v237 offset:16384
	ds_read_b128 v[154:157], v237 offset:17408
	ds_read_b128 v[158:161], v237 offset:18432
	ds_read_b128 v[162:165], v237 offset:19456
	ds_read_b128 v[178:181], v237 offset:20480
	ds_read_b128 v[182:185], v237 offset:21504
	ds_read_b128 v[186:189], v237 offset:22528
	ds_read_b128 v[190:193], v237 offset:23552
	s_add_i32 s60, s60, s45
	v_lshl_add_u64 v[194:195], s[58:59], 0, v[202:203]
	s_add_u32 s58, s58, 0x40000
	s_mov_b32 m0, s60
	s_addc_u32 s59, s59, 0
	global_load_lds_dwordx4 v[194:195], off
	s_add_i32 m0, s60, 0x2000
	v_lshl_add_u64 v[194:195], s[58:59], 0, v[202:203]
	s_add_u32 s58, s40, 0x80000
	s_addc_u32 s59, s41, 0
	global_load_lds_dwordx4 v[194:195], off
	s_add_i32 s60, s61, s45
	v_lshl_add_u64 v[194:195], s[58:59], 0, v[202:203]
	s_add_u32 s58, s58, 0x40000
	s_mov_b32 m0, s60
	s_addc_u32 s59, s59, 0
	global_load_lds_dwordx4 v[194:195], off
	s_add_i32 m0, s60, 0x2000
	v_lshl_add_u64 v[194:195], s[58:59], 0, v[202:203]
	s_mov_b64 s[58:59], s[42:43]
	global_load_lds_dwordx4 v[194:195], off
	s_mov_b32 m0, s46
	v_lshl_add_u64 v[194:195], s[58:59], 0, v[208:209]
	s_add_u32 s58, s58, 0x40000
	s_addc_u32 s59, s59, 0
	global_load_lds_dwordx4 v[194:195], off
	s_mov_b32 m0, s47
	v_lshl_add_u64 v[194:195], s[58:59], 0, v[208:209]
	global_load_lds_dwordx4 v[194:195], off
	s_waitcnt vmcnt(16)
	s_waitcnt lgkmcnt(0)
	s_barrier
	v_mfma_f32_16x16x32_bf16 v[78:81], v[42:45], v[142:145], 0
	v_mfma_f32_16x16x32_bf16 v[74:77], v[66:69], v[142:145], 0
	v_mfma_f32_16x16x32_bf16 v[54:57], v[42:45], v[158:161], 0
	v_mfma_f32_16x16x32_bf16 v[50:53], v[66:69], v[158:161], 0
	v_mfma_f32_16x16x32_bf16 v[30:33], v[42:45], v[178:181], 0
	v_mfma_f32_16x16x32_bf16 v[26:29], v[66:69], v[178:181], 0
	v_mfma_f32_16x16x32_bf16 v[14:17], v[42:45], v[186:189], 0
	v_mfma_f32_16x16x32_bf16 v[10:13], v[66:69], v[186:189], 0
	v_mfma_f32_16x16x32_bf16 v[78:81], v[46:49], v[154:157], v[78:81]
	v_mfma_f32_16x16x32_bf16 v[74:77], v[70:73], v[154:157], v[74:77]
	v_mfma_f32_16x16x32_bf16 v[54:57], v[46:49], v[162:165], v[54:57]
	v_mfma_f32_16x16x32_bf16 v[50:53], v[70:73], v[162:165], v[50:53]
	v_mfma_f32_16x16x32_bf16 v[30:33], v[46:49], v[182:185], v[30:33]
	v_mfma_f32_16x16x32_bf16 v[26:29], v[70:73], v[182:185], v[26:29]
	v_mfma_f32_16x16x32_bf16 v[14:17], v[46:49], v[190:193], v[14:17]
	v_mfma_f32_16x16x32_bf16 v[10:13], v[70:73], v[190:193], v[10:13]
	v_mfma_f32_16x16x32_bf16 v[38:41], v[86:89], v[158:161], 0
	v_mfma_f32_16x16x32_bf16 v[34:37], v[106:109], v[158:161], 0
	v_mfma_f32_16x16x32_bf16 v[22:25], v[86:89], v[178:181], 0
	v_mfma_f32_16x16x32_bf16 v[18:21], v[106:109], v[178:181], 0
	v_mfma_f32_16x16x32_bf16 v[6:9], v[86:89], v[186:189], v[6:9]
	v_mfma_f32_16x16x32_bf16 v[2:5], v[106:109], v[186:189], v[2:5]
	v_mfma_f32_16x16x32_bf16 v[42:45], v[86:89], v[142:145], 0
	v_mfma_f32_16x16x32_bf16 v[46:49], v[106:109], v[142:145], 0
	v_mfma_f32_16x16x32_bf16 v[38:41], v[90:93], v[162:165], v[38:41]
	v_mfma_f32_16x16x32_bf16 v[34:37], v[110:113], v[162:165], v[34:37]
	v_mfma_f32_16x16x32_bf16 v[22:25], v[90:93], v[182:185], v[22:25]
	v_mfma_f32_16x16x32_bf16 v[18:21], v[110:113], v[182:185], v[18:21]
	v_mfma_f32_16x16x32_bf16 v[6:9], v[90:93], v[190:193], v[6:9]
	v_mfma_f32_16x16x32_bf16 v[2:5], v[110:113], v[190:193], v[2:5]
	v_mfma_f32_16x16x32_bf16 v[42:45], v[90:93], v[154:157], v[42:45]
	v_mfma_f32_16x16x32_bf16 v[46:49], v[110:113], v[154:157], v[46:49]
	s_barrier
	s_add_i32 s58, 0, 0x18000
	s_add_i32 s59, 0, 0x1c000
	v_add_u32_e32 v70, s58, v207
	v_add_u32_e32 v110, s59, v207
	ds_read_b128 v[58:61], v70
	ds_read_b128 v[62:65], v70 offset:1024
	ds_read_b128 v[66:69], v70 offset:2048
	ds_read_b128 v[70:73], v70 offset:3072
	ds_read_b128 v[86:89], v110
	ds_read_b128 v[90:93], v110 offset:1024
	ds_read_b128 v[106:109], v110 offset:2048
	ds_read_b128 v[110:113], v110 offset:3072
	s_add_u32 s42, s42, 0x80000
	s_addc_u32 s43, s43, 0
	ds_read_b128 v[142:145], v237 offset:32768
	ds_read_b128 v[154:157], v237 offset:33792
	ds_read_b128 v[158:161], v237 offset:34816
	ds_read_b128 v[178:181], v237 offset:35840
	ds_read_b128 v[182:185], v237 offset:36864
	ds_read_b128 v[186:189], v237 offset:37888
	ds_read_b128 v[190:193], v237 offset:38912
	ds_read_b128 v[194:197], v237 offset:39936
	s_mov_b32 m0, s48
	v_lshl_add_u64 v[162:163], s[42:43], 0, v[208:209]
	s_add_u32 s42, s42, 0x40000
	s_addc_u32 s43, s43, 0
	global_load_lds_dwordx4 v[162:163], off
	s_mov_b32 m0, s49
	v_lshl_add_u64 v[162:163], s[42:43], 0, v[208:209]
	global_load_lds_dwordx4 v[162:163], off
	s_waitcnt vmcnt(8)
	s_waitcnt lgkmcnt(0)
	s_barrier
	v_mfma_f32_16x16x32_bf16 v[162:165], v[58:61], v[142:145], v[174:177]
	v_mfma_f32_16x16x32_bf16 v[174:177], v[62:65], v[154:157], v[162:165]
	v_mfma_f32_16x16x32_bf16 v[162:165], v[66:69], v[142:145], v[170:173]
	v_mfma_f32_16x16x32_bf16 v[150:153], v[58:61], v[158:161], v[150:153]
	v_mfma_f32_16x16x32_bf16 v[146:149], v[66:69], v[158:161], v[146:149]
	v_mfma_f32_16x16x32_bf16 v[126:129], v[58:61], v[182:185], v[126:129]
	v_mfma_f32_16x16x32_bf16 v[122:125], v[66:69], v[182:185], v[122:125]
	v_mfma_f32_16x16x32_bf16 v[102:105], v[58:61], v[190:193], v[102:105]
	v_mfma_f32_16x16x32_bf16 v[98:101], v[66:69], v[190:193], v[98:101]
	v_mfma_f32_16x16x32_bf16 v[170:173], v[70:73], v[154:157], v[162:165]
	v_mfma_f32_16x16x32_bf16 v[150:153], v[62:65], v[178:181], v[150:153]
	v_mfma_f32_16x16x32_bf16 v[146:149], v[70:73], v[178:181], v[146:149]
	v_mfma_f32_16x16x32_bf16 v[126:129], v[62:65], v[186:189], v[126:129]
	v_mfma_f32_16x16x32_bf16 v[122:125], v[70:73], v[186:189], v[122:125]
	v_mfma_f32_16x16x32_bf16 v[102:105], v[62:65], v[194:197], v[102:105]
	v_mfma_f32_16x16x32_bf16 v[98:101], v[70:73], v[194:197], v[98:101]
	v_mfma_f32_16x16x32_bf16 v[162:165], v[86:89], v[142:145], v[166:169]
	v_mfma_f32_16x16x32_bf16 v[130:133], v[106:109], v[142:145], v[130:133]
	v_mfma_f32_16x16x32_bf16 v[166:169], v[90:93], v[154:157], v[162:165]
	v_mfma_f32_16x16x32_bf16 v[162:165], v[110:113], v[154:157], v[130:133]
	v_mfma_f32_16x16x32_bf16 v[130:133], v[86:89], v[158:161], v[134:137]
	v_mfma_f32_16x16x32_bf16 v[142:145], v[90:93], v[178:181], v[130:133]
	v_mfma_f32_16x16x32_bf16 v[130:133], v[106:109], v[158:161], v[138:141]
	v_mfma_f32_16x16x32_bf16 v[118:121], v[86:89], v[182:185], v[118:121]
	v_mfma_f32_16x16x32_bf16 v[114:117], v[106:109], v[182:185], v[114:117]
	v_mfma_f32_16x16x32_bf16 v[94:97], v[86:89], v[190:193], v[94:97]
	v_mfma_f32_16x16x32_bf16 v[82:85], v[106:109], v[190:193], v[82:85]
	v_mfma_f32_16x16x32_bf16 v[138:141], v[110:113], v[178:181], v[130:133]
	v_mfma_f32_16x16x32_bf16 v[118:121], v[90:93], v[186:189], v[118:121]
	v_mfma_f32_16x16x32_bf16 v[114:117], v[110:113], v[186:189], v[114:117]
	v_mfma_f32_16x16x32_bf16 v[94:97], v[90:93], v[194:197], v[94:97]
	v_mfma_f32_16x16x32_bf16 v[82:85], v[110:113], v[194:197], v[82:85]
	s_barrier
	s_add_u32 s42, s40, 0x80
	s_addc_u32 s43, s41, 0
	ds_read_b128 v[130:133], v237 offset:49152
	ds_read_b128 v[134:137], v237 offset:50176
	ds_read_b128 v[154:157], v237 offset:51200
	ds_read_b128 v[158:161], v237 offset:52224
	ds_read_b128 v[178:181], v237 offset:53248
	ds_read_b128 v[182:185], v237 offset:54272
	ds_read_b128 v[186:189], v237 offset:55296
	ds_read_b128 v[190:193], v237 offset:56320
	s_add_i32 s58, s58, s45
	v_lshl_add_u64 v[194:195], s[42:43], 0, v[202:203]
	s_mov_b32 m0, s58
	s_add_u32 s42, s42, 0x40000
	global_load_lds_dwordx4 v[194:195], off
	s_addc_u32 s43, s43, 0
	s_add_i32 m0, s58, 0x2000
	s_add_u32 s40, s40, 0x80080
	s_addc_u32 s41, s41, 0
	v_lshl_add_u64 v[194:195], s[42:43], 0, v[202:203]
	global_load_lds_dwordx4 v[194:195], off
	s_add_i32 s42, s59, s45
	v_lshl_add_u64 v[194:195], s[40:41], 0, v[202:203]
	s_add_u32 s40, s40, 0x40000
	s_mov_b32 m0, s42
	s_addc_u32 s41, s41, 0
	global_load_lds_dwordx4 v[194:195], off
	s_add_i32 m0, s42, 0x2000
	v_lshl_add_u64 v[194:195], s[40:41], 0, v[202:203]
	global_load_lds_dwordx4 v[194:195], off
	s_mov_b32 m0, s50
	v_lshl_add_u64 v[194:195], s[38:39], 0, v[208:209]
	s_add_u32 s38, s38, 0x40000
	s_addc_u32 s39, s39, 0
	global_load_lds_dwordx4 v[194:195], off
	s_mov_b32 m0, s51
	v_lshl_add_u64 v[194:195], s[38:39], 0, v[208:209]
	global_load_lds_dwordx4 v[194:195], off
	s_waitcnt vmcnt(8)
	s_waitcnt lgkmcnt(0)
	s_barrier
	v_mfma_f32_16x16x32_bf16 v[78:81], v[58:61], v[130:133], v[78:81]
	v_mfma_f32_16x16x32_bf16 v[74:77], v[66:69], v[130:133], v[74:77]
	v_mfma_f32_16x16x32_bf16 v[54:57], v[58:61], v[154:157], v[54:57]
	v_mfma_f32_16x16x32_bf16 v[50:53], v[66:69], v[154:157], v[50:53]
	v_mfma_f32_16x16x32_bf16 v[30:33], v[58:61], v[178:181], v[30:33]
	v_mfma_f32_16x16x32_bf16 v[26:29], v[66:69], v[178:181], v[26:29]
	v_mfma_f32_16x16x32_bf16 v[14:17], v[58:61], v[186:189], v[14:17]
	v_mfma_f32_16x16x32_bf16 v[10:13], v[66:69], v[186:189], v[10:13]
	v_mfma_f32_16x16x32_bf16 v[78:81], v[62:65], v[134:137], v[78:81]
	v_mfma_f32_16x16x32_bf16 v[74:77], v[70:73], v[134:137], v[74:77]
	v_mfma_f32_16x16x32_bf16 v[54:57], v[62:65], v[158:161], v[54:57]
	v_mfma_f32_16x16x32_bf16 v[50:53], v[70:73], v[158:161], v[50:53]
	v_mfma_f32_16x16x32_bf16 v[30:33], v[62:65], v[182:185], v[30:33]
	v_mfma_f32_16x16x32_bf16 v[26:29], v[70:73], v[182:185], v[26:29]
	v_mfma_f32_16x16x32_bf16 v[14:17], v[62:65], v[190:193], v[14:17]
	v_mfma_f32_16x16x32_bf16 v[10:13], v[70:73], v[190:193], v[10:13]
	v_mfma_f32_16x16x32_bf16 v[42:45], v[86:89], v[130:133], v[42:45]
	v_mfma_f32_16x16x32_bf16 v[62:65], v[90:93], v[134:137], v[42:45]
	v_mfma_f32_16x16x32_bf16 v[42:45], v[106:109], v[130:133], v[46:49]
	v_mfma_f32_16x16x32_bf16 v[38:41], v[86:89], v[154:157], v[38:41]
	v_mfma_f32_16x16x32_bf16 v[34:37], v[106:109], v[154:157], v[34:37]
	v_mfma_f32_16x16x32_bf16 v[22:25], v[86:89], v[178:181], v[22:25]
	v_mfma_f32_16x16x32_bf16 v[18:21], v[106:109], v[178:181], v[18:21]
	v_mfma_f32_16x16x32_bf16 v[6:9], v[86:89], v[186:189], v[6:9]
	v_mfma_f32_16x16x32_bf16 v[2:5], v[106:109], v[186:189], v[2:5]
	v_mfma_f32_16x16x32_bf16 v[58:61], v[110:113], v[134:137], v[42:45]
	v_mfma_f32_16x16x32_bf16 v[38:41], v[90:93], v[158:161], v[38:41]
	v_mfma_f32_16x16x32_bf16 v[34:37], v[110:113], v[158:161], v[34:37]
	v_mfma_f32_16x16x32_bf16 v[22:25], v[90:93], v[182:185], v[22:25]
	v_mfma_f32_16x16x32_bf16 v[18:21], v[110:113], v[182:185], v[18:21]
	v_mfma_f32_16x16x32_bf16 v[6:9], v[90:93], v[190:193], v[6:9]
	v_mfma_f32_16x16x32_bf16 v[2:5], v[110:113], v[190:193], v[2:5]
	s_barrier
	s_add_i32 s57, s57, 2
	s_add_u32 s19, s19, 0x100
	s_addc_u32 s54, s54, 0
	s_add_u32 s55, s55, 0x100
	s_addc_u32 s56, s56, 0
	s_cmp_gt_u32 s57, 29
	s_cbranch_scc1 .Lpeel0_exit

.LBB0_997:
	s_or_b64 exec, exec, s[4:5]
	v_readlane_b32 s4, v249, 4
	v_readlane_b32 s6, v248, 12
	v_readlane_b32 s5, v249, 5
	s_waitcnt lgkmcnt(0)
	v_mov_b32_e32 v2, v0
	v_readlane_b32 s7, v248, 13
	s_barrier
	s_mul_hi_u32 s58, s84, 0x8600000
	s_mul_i32 s59, s84, 0x8600000
	s_and_b64 vcc, exec, s[6:7]
	v_readfirstlane_b32 s24, v2
	s_cbranch_vccz .LBB0_1033
	v_bfe_i32 v4, v2, 27, 1
	v_lshlrev_b32_e32 v3, 4, v2
	v_lshrrev_b32_e32 v4, 22, v4
	v_add_u32_e32 v4, v3, v4
	s_load_dwordx4 s[16:19], s[4:5], 0xb8
	s_nop 0
	s_load_dwordx2 s[4:5], s[4:5], 0x78
	v_and_b32_e32 v4, 0xfffffc00, v4
	v_sub_u32_e32 v3, v3, v4
	v_ashrrev_i32_e32 v5, 31, v2
	v_lshrrev_b32_e32 v4, 4, v3
	v_lshrrev_b32_e32 v5, 26, v5
	v_bitop3_b32 v4, v4, v3, 32 bitop3:0x6c
	v_ashrrev_i32_e32 v3, 31, v3
	v_add_u32_e32 v5, v2, v5
	s_waitcnt lgkmcnt(0)
	s_add_u32 s6, s18, s59
	v_lshrrev_b32_e32 v3, 26, v3
	v_ashrrev_i32_e32 v5, 6, v5
	s_addc_u32 s7, s19, s58
	v_add_u32_e32 v3, v4, v3
	v_lshlrev_b32_e32 v6, 3, v5
	s_add_u32 s30, s6, 0x1500000
	v_ashrrev_i32_e32 v3, 6, v3
	v_and_b32_e32 v6, -16, v6
	s_addc_u32 s31, s7, 0
	s_ashr_i32 s25, s24, 6
	v_add_u32_e32 v6, v3, v6
	s_ashr_i32 s26, s24, 8
	s_lshl_b32 s48, s25, 10
	v_lshrrev_b32_e32 v8, 2, v6
	v_readlane_b32 s6, v248, 16
	v_and_b32_e32 v8, 4, v8
	v_readlane_b32 s7, v248, 17
	s_add_u32 s44, s16, s6
	v_lshlrev_b32_e32 v7, 1, v6
	v_and_or_b32 v8, v3, 3, v8
	v_mul_i32_i24_e32 v3, 64, v3
	s_addc_u32 s45, s17, s7
	v_readlane_b32 s6, v248, 18
	v_and_b32_e32 v7, 24, v7
	v_lshlrev_b32_e32 v5, 5, v5
	v_sub_u32_e32 v3, v4, v3
	s_add_u32 s10, s30, s6
	v_readlane_b32 s6, v248, 19
	v_and_b32_e32 v4, 0x7fffe0, v6
	v_and_b32_e32 v5, 32, v5
	v_ashrrev_i16_sdwa v3, v229, sext(v3) dst_sel:DWORD dst_unused:UNUSED_PAD src0_sel:DWORD src1_sel:BYTE_0
	s_addc_u32 s11, s31, s6
	v_or3_b32 v4, v7, v8, v4
	v_add_u32_sdwa v3, v5, sext(v3) dst_sel:DWORD dst_unused:UNUSED_PAD src0_sel:DWORD src1_sel:WORD_0
	v_mul_u32_u24_e32 v4, 0x600, v4
	s_mov_b64 s[6:7], s[10:11]
	s_add_i32 s49, s48, 0
	v_add_lshl_u32 v202, v4, v3, 1
	s_add_i32 m0, s49, 0x10000
	v_lshlrev_b32_e32 v4, 12, v6
	global_load_lds_dwordx4 v202, s[6:7]
	s_add_u32 s6, s6, 0x30000
	s_addc_u32 s7, s7, 0
	s_add_i32 m0, s49, 0x12000
	v_lshl_add_u32 v158, v3, 1, v4
	global_load_lds_dwordx4 v202, s[6:7]
	s_add_u32 s6, s10, 0x60000
	s_addc_u32 s7, s11, 0
	s_add_i32 m0, s49, 0x14000
	s_nop 0
	global_load_lds_dwordx4 v202, s[6:7]
	s_add_u32 s6, s6, 0x30000
	s_addc_u32 s7, s7, 0
	s_add_i32 m0, s49, 0x16000
	s_nop 0
	global_load_lds_dwordx4 v202, s[6:7]
	s_mov_b64 s[6:7], s[44:45]
	s_mov_b32 m0, s49
	s_nop 0
	global_load_lds_dwordx4 v158, s[6:7]
	s_add_u32 s6, s6, 0x40000
	s_addc_u32 s7, s7, 0
	s_add_i32 s50, s49, 0x2000
	s_mov_b32 m0, s50
	s_nop 0
	global_load_lds_dwordx4 v158, s[6:7]
	s_add_u32 s6, s44, 0x80000
	s_addc_u32 s7, s45, 0
	s_add_i32 s51, s49, 0x4000
	s_mov_b32 m0, s51
	s_nop 0
	global_load_lds_dwordx4 v158, s[6:7]
	s_add_u32 s6, s6, 0x40000
	s_addc_u32 s7, s7, 0
	s_add_i32 s52, s49, 0x6000
	s_mov_b32 m0, s52
	s_nop 0
	global_load_lds_dwordx4 v158, s[6:7]
	s_add_u32 s6, s10, 0x80
	s_addc_u32 s7, s11, 0
	s_add_i32 m0, s49, 0x18000
	s_nop 0
	global_load_lds_dwordx4 v202, s[6:7]
	s_add_u32 s6, s6, 0x30000
	s_addc_u32 s7, s7, 0
	s_add_i32 m0, s49, 0x1a000
	s_nop 0
	global_load_lds_dwordx4 v202, s[6:7]
	s_add_u32 s6, s44, 0x80
	s_addc_u32 s7, s45, 0
	s_add_i32 s53, s49, 0x8000
	s_mov_b32 m0, s53
	s_nop 0
	global_load_lds_dwordx4 v158, s[6:7]
	s_add_u32 s6, s6, 0x40000
	s_addc_u32 s7, s7, 0
	s_add_i32 s54, s49, 0xa000
	s_mov_b32 m0, s54
	s_nop 0
	global_load_lds_dwordx4 v158, s[6:7]
	s_add_u32 s6, s10, 0x60080
	s_addc_u32 s7, s11, 0
	s_add_i32 m0, s49, 0x1c000
	s_nop 0
	global_load_lds_dwordx4 v202, s[6:7]
	s_add_u32 s6, s6, 0x30000
	s_addc_u32 s7, s7, 0
	s_add_i32 m0, s49, 0x1e000
	s_cmp_eq_u32 s26, 1
	global_load_lds_dwordx4 v202, s[6:7]
	s_waitcnt vmcnt(0)
	s_cselect_b64 s[6:7], -1, 0
	s_cmp_lg_u32 s26, 1
	s_cbranch_scc1 .LBB0_1000
	s_barrier

.LBB0_1025:
	s_mov_b32 s10, 0
	v_mov_b32_e32 v2, 0
	v_mov_b32_e32 v3, 0
	v_mov_b32_e32 v4, 0
	v_mov_b32_e32 v5, 0
	v_mov_b32_e32 v6, 0
	v_mov_b32_e32 v7, 0
	v_mov_b32_e32 v8, 0
	v_mov_b32_e32 v9, 0
	s_waitcnt vmcnt(14)
	s_add_i32 s28, s10, 2
	s_cmp_eq_u32 s71, s10
	s_cselect_b32 s46, s4, s74
	s_cselect_b32 s47, s5, s75
	s_cselect_b32 s44, s42, s72
	s_cselect_b32 s45, s43, s73
	s_add_u32 s10, s46, 0x80
	s_addc_u32 s11, s47, 0
	s_add_i32 s29, 0, 0x10000
	s_add_i32 s78, 0, 0x14000
	v_add_u32_e32 v142, s29, v179
	v_add_u32_e32 v160, s78, v179
	ds_read_b128 v[130:133], v142
	ds_read_b128 v[134:137], v142 offset:1024
	ds_read_b128 v[138:141], v142 offset:2048
	ds_read_b128 v[142:145], v142 offset:3072
	ds_read_b128 v[146:149], v160
	ds_read_b128 v[150:153], v160 offset:1024
	ds_read_b128 v[154:157], v160 offset:2048
	ds_read_b128 v[160:163], v160 offset:3072
	s_add_u32 s76, s74, 0x7ff80
	v_add_u32_e32 v200, 0, v178
	s_addc_u32 s77, s75, 0
	ds_read_b128 v[164:167], v200
	ds_read_b128 v[168:171], v200 offset:1024
	ds_read_b128 v[172:175], v200 offset:2048
	ds_read_b128 v[180:183], v200 offset:3072
	ds_read_b128 v[184:187], v200 offset:4096
	ds_read_b128 v[188:191], v200 offset:5120
	ds_read_b128 v[192:195], v200 offset:6144
	ds_read_b128 v[196:199], v200 offset:7168
	s_add_i32 m0, s49, 0xc000
	v_lshl_add_u64 v[176:177], s[76:77], 0, v[158:159]
	s_add_u32 s76, s76, 0x40000
	s_addc_u32 s77, s77, 0
	global_load_lds_dwordx4 v[176:177], off
	s_add_i32 m0, s49, 0xe000
	v_lshl_add_u64 v[176:177], s[76:77], 0, v[158:159]
	global_load_lds_dwordx4 v[176:177], off
	s_waitcnt vmcnt(16)
	s_waitcnt lgkmcnt(0)
	s_barrier
	v_mfma_i32_16x16x64_i8 v[126:129], v[130:133], v[164:167], 0
	v_mfma_i32_16x16x64_i8 v[122:125], v[138:141], v[164:167], 0
	v_mfma_i32_16x16x64_i8 v[118:121], v[130:133], v[172:175], 0
	v_mfma_i32_16x16x64_i8 v[114:117], v[138:141], v[172:175], 0
	v_mfma_i32_16x16x64_i8 v[102:105], v[130:133], v[184:187], 0
	v_mfma_i32_16x16x64_i8 v[98:101], v[138:141], v[184:187], 0
	v_mfma_i32_16x16x64_i8 v[86:89], v[130:133], v[192:195], 0
	v_mfma_i32_16x16x64_i8 v[82:85], v[138:141], v[192:195], 0
	v_mfma_i32_16x16x64_i8 v[126:129], v[134:137], v[168:171], v[126:129]
	v_mfma_i32_16x16x64_i8 v[122:125], v[142:145], v[168:171], v[122:125]
	v_mfma_i32_16x16x64_i8 v[118:121], v[134:137], v[180:183], v[118:121]
	v_mfma_i32_16x16x64_i8 v[114:117], v[142:145], v[180:183], v[114:117]
	v_mfma_i32_16x16x64_i8 v[102:105], v[134:137], v[188:191], v[102:105]
	v_mfma_i32_16x16x64_i8 v[98:101], v[142:145], v[188:191], v[98:101]
	v_mfma_i32_16x16x64_i8 v[86:89], v[134:137], v[196:199], v[86:89]
	v_mfma_i32_16x16x64_i8 v[82:85], v[142:145], v[196:199], v[82:85]
	v_mfma_i32_16x16x64_i8 v[110:113], v[146:149], v[164:167], 0
	v_mfma_i32_16x16x64_i8 v[106:109], v[154:157], v[164:167], 0
	v_mfma_i32_16x16x64_i8 v[94:97], v[146:149], v[172:175], 0
	v_mfma_i32_16x16x64_i8 v[90:93], v[154:157], v[172:175], 0
	v_mfma_i32_16x16x64_i8 v[78:81], v[146:149], v[184:187], 0
	v_mfma_i32_16x16x64_i8 v[74:77], v[154:157], v[184:187], 0
	v_mfma_i32_16x16x64_i8 v[70:73], v[146:149], v[192:195], 0
	v_mfma_i32_16x16x64_i8 v[66:69], v[154:157], v[192:195], 0
	v_mfma_i32_16x16x64_i8 v[110:113], v[150:153], v[168:171], v[110:113]
	v_mfma_i32_16x16x64_i8 v[106:109], v[160:163], v[168:171], v[106:109]
	v_mfma_i32_16x16x64_i8 v[94:97], v[150:153], v[180:183], v[94:97]
	v_mfma_i32_16x16x64_i8 v[90:93], v[160:163], v[180:183], v[90:93]
	v_mfma_i32_16x16x64_i8 v[78:81], v[150:153], v[188:191], v[78:81]
	v_mfma_i32_16x16x64_i8 v[74:77], v[160:163], v[188:191], v[74:77]
	v_mfma_i32_16x16x64_i8 v[70:73], v[150:153], v[196:199], v[70:73]
	v_mfma_i32_16x16x64_i8 v[66:69], v[160:163], v[196:199], v[66:69]
	s_barrier
	s_mov_b64 s[76:77], s[44:45]
	ds_read_b128 v[164:167], v200 offset:16384
	ds_read_b128 v[168:171], v200 offset:17408
	ds_read_b128 v[172:175], v200 offset:18432
	ds_read_b128 v[180:183], v200 offset:19456
	ds_read_b128 v[184:187], v200 offset:20480
	ds_read_b128 v[188:191], v200 offset:21504
	ds_read_b128 v[192:195], v200 offset:22528
	ds_read_b128 v[196:199], v200 offset:23552
	s_add_i32 s29, s29, s48
	v_lshl_add_u64 v[176:177], s[76:77], 0, v[202:203]
	s_add_u32 s76, s76, 0x30000
	s_mov_b32 m0, s29
	s_addc_u32 s77, s77, 0
	global_load_lds_dwordx4 v[176:177], off
	s_add_i32 m0, s29, 0x2000
	v_lshl_add_u64 v[176:177], s[76:77], 0, v[202:203]
	s_add_u32 s76, s44, 0x60000
	s_addc_u32 s77, s45, 0
	global_load_lds_dwordx4 v[176:177], off
	s_add_i32 s29, s78, s48
	v_lshl_add_u64 v[176:177], s[76:77], 0, v[202:203]
	s_add_u32 s76, s76, 0x30000
	s_mov_b32 m0, s29
	s_addc_u32 s77, s77, 0
	global_load_lds_dwordx4 v[176:177], off
	s_add_i32 m0, s29, 0x2000
	v_lshl_add_u64 v[176:177], s[76:77], 0, v[202:203]
	s_mov_b64 s[76:77], s[46:47]
	global_load_lds_dwordx4 v[176:177], off
	s_mov_b32 m0, s49
	v_lshl_add_u64 v[176:177], s[76:77], 0, v[158:159]
	s_add_u32 s76, s76, 0x40000
	s_addc_u32 s77, s77, 0
	global_load_lds_dwordx4 v[176:177], off
	s_mov_b32 m0, s50
	v_lshl_add_u64 v[176:177], s[76:77], 0, v[158:159]
	global_load_lds_dwordx4 v[176:177], off
	s_waitcnt vmcnt(22)
	s_waitcnt lgkmcnt(0)
	s_barrier
	v_mfma_i32_16x16x64_i8 v[62:65], v[130:133], v[164:167], 0
	v_mfma_i32_16x16x64_i8 v[58:61], v[138:141], v[164:167], 0
	v_mfma_i32_16x16x64_i8 v[54:57], v[130:133], v[172:175], 0
	v_mfma_i32_16x16x64_i8 v[50:53], v[138:141], v[172:175], 0
	v_mfma_i32_16x16x64_i8 v[38:41], v[130:133], v[184:187], 0
	v_mfma_i32_16x16x64_i8 v[34:37], v[138:141], v[184:187], 0
	v_mfma_i32_16x16x64_i8 v[14:17], v[130:133], v[192:195], 0
	v_mfma_i32_16x16x64_i8 v[10:13], v[138:141], v[192:195], 0
	v_mfma_i32_16x16x64_i8 v[62:65], v[134:137], v[168:171], v[62:65]
	v_mfma_i32_16x16x64_i8 v[58:61], v[142:145], v[168:171], v[58:61]
	v_mfma_i32_16x16x64_i8 v[54:57], v[134:137], v[180:183], v[54:57]
	v_mfma_i32_16x16x64_i8 v[50:53], v[142:145], v[180:183], v[50:53]
	v_mfma_i32_16x16x64_i8 v[38:41], v[134:137], v[188:191], v[38:41]
	v_mfma_i32_16x16x64_i8 v[34:37], v[142:145], v[188:191], v[34:37]
	v_mfma_i32_16x16x64_i8 v[14:17], v[134:137], v[196:199], v[14:17]
	v_mfma_i32_16x16x64_i8 v[10:13], v[142:145], v[196:199], v[10:13]
	v_mfma_i32_16x16x64_i8 v[46:49], v[146:149], v[164:167], 0
	v_mfma_i32_16x16x64_i8 v[42:45], v[154:157], v[164:167], 0
	v_mfma_i32_16x16x64_i8 v[30:33], v[146:149], v[172:175], 0
	v_mfma_i32_16x16x64_i8 v[26:29], v[154:157], v[172:175], 0
	v_mfma_i32_16x16x64_i8 v[22:25], v[146:149], v[184:187], 0
	v_mfma_i32_16x16x64_i8 v[18:21], v[154:157], v[184:187], 0
	v_mfma_i32_16x16x64_i8 v[6:9], v[146:149], v[192:195], v[6:9]
	v_mfma_i32_16x16x64_i8 v[2:5], v[154:157], v[192:195], v[2:5]
	v_mfma_i32_16x16x64_i8 v[46:49], v[150:153], v[168:171], v[46:49]
	v_mfma_i32_16x16x64_i8 v[42:45], v[160:163], v[168:171], v[42:45]
	v_mfma_i32_16x16x64_i8 v[30:33], v[150:153], v[180:183], v[30:33]
	v_mfma_i32_16x16x64_i8 v[26:29], v[160:163], v[180:183], v[26:29]
	v_mfma_i32_16x16x64_i8 v[22:25], v[150:153], v[188:191], v[22:25]
	v_mfma_i32_16x16x64_i8 v[18:21], v[160:163], v[188:191], v[18:21]
	v_mfma_i32_16x16x64_i8 v[6:9], v[150:153], v[196:199], v[6:9]
	v_mfma_i32_16x16x64_i8 v[2:5], v[160:163], v[196:199], v[2:5]
	s_barrier
	s_add_i32 s29, 0, 0x18000
	s_add_i32 s76, 0, 0x1c000
	v_add_u32_e32 v142, s29, v179
	v_add_u32_e32 v160, s76, v179
	ds_read_b128 v[130:133], v142
	ds_read_b128 v[134:137], v142 offset:1024
	ds_read_b128 v[138:141], v142 offset:2048
	ds_read_b128 v[142:145], v142 offset:3072
	ds_read_b128 v[146:149], v160
	ds_read_b128 v[150:153], v160 offset:1024
	ds_read_b128 v[154:157], v160 offset:2048
	ds_read_b128 v[160:163], v160 offset:3072
	s_add_u32 s46, s46, 0x80000
	s_addc_u32 s47, s47, 0
	ds_read_b128 v[164:167], v200 offset:32768
	ds_read_b128 v[168:171], v200 offset:33792
	ds_read_b128 v[172:175], v200 offset:34816
	ds_read_b128 v[180:183], v200 offset:35840
	ds_read_b128 v[184:187], v200 offset:36864
	ds_read_b128 v[188:191], v200 offset:37888
	ds_read_b128 v[192:195], v200 offset:38912
	ds_read_b128 v[196:199], v200 offset:39936
	s_mov_b32 m0, s51
	v_lshl_add_u64 v[176:177], s[46:47], 0, v[158:159]
	s_add_u32 s46, s46, 0x40000
	s_addc_u32 s47, s47, 0
	global_load_lds_dwordx4 v[176:177], off
	s_mov_b32 m0, s52
	v_lshl_add_u64 v[176:177], s[46:47], 0, v[158:159]
	global_load_lds_dwordx4 v[176:177], off
	s_waitcnt vmcnt(8)
	s_waitcnt lgkmcnt(0)
	s_barrier
	v_mfma_i32_16x16x64_i8 v[126:129], v[130:133], v[164:167], v[126:129]
	v_mfma_i32_16x16x64_i8 v[122:125], v[138:141], v[164:167], v[122:125]
	v_mfma_i32_16x16x64_i8 v[118:121], v[130:133], v[172:175], v[118:121]
	v_mfma_i32_16x16x64_i8 v[114:117], v[138:141], v[172:175], v[114:117]
	v_mfma_i32_16x16x64_i8 v[102:105], v[130:133], v[184:187], v[102:105]
	v_mfma_i32_16x16x64_i8 v[98:101], v[138:141], v[184:187], v[98:101]
	v_mfma_i32_16x16x64_i8 v[86:89], v[130:133], v[192:195], v[86:89]
	v_mfma_i32_16x16x64_i8 v[82:85], v[138:141], v[192:195], v[82:85]
	v_mfma_i32_16x16x64_i8 v[126:129], v[134:137], v[168:171], v[126:129]
	v_mfma_i32_16x16x64_i8 v[122:125], v[142:145], v[168:171], v[122:125]
	v_mfma_i32_16x16x64_i8 v[118:121], v[134:137], v[180:183], v[118:121]
	v_mfma_i32_16x16x64_i8 v[114:117], v[142:145], v[180:183], v[114:117]
	v_mfma_i32_16x16x64_i8 v[102:105], v[134:137], v[188:191], v[102:105]
	v_mfma_i32_16x16x64_i8 v[98:101], v[142:145], v[188:191], v[98:101]
	v_mfma_i32_16x16x64_i8 v[86:89], v[134:137], v[196:199], v[86:89]
	v_mfma_i32_16x16x64_i8 v[82:85], v[142:145], v[196:199], v[82:85]
	v_mfma_i32_16x16x64_i8 v[110:113], v[146:149], v[164:167], v[110:113]
	v_mfma_i32_16x16x64_i8 v[106:109], v[154:157], v[164:167], v[106:109]
	v_mfma_i32_16x16x64_i8 v[94:97], v[146:149], v[172:175], v[94:97]
	v_mfma_i32_16x16x64_i8 v[90:93], v[154:157], v[172:175], v[90:93]
	v_mfma_i32_16x16x64_i8 v[78:81], v[146:149], v[184:187], v[78:81]
	v_mfma_i32_16x16x64_i8 v[74:77], v[154:157], v[184:187], v[74:77]
	v_mfma_i32_16x16x64_i8 v[70:73], v[146:149], v[192:195], v[70:73]
	v_mfma_i32_16x16x64_i8 v[66:69], v[154:157], v[192:195], v[66:69]
	v_mfma_i32_16x16x64_i8 v[110:113], v[150:153], v[168:171], v[110:113]
	v_mfma_i32_16x16x64_i8 v[106:109], v[160:163], v[168:171], v[106:109]
	v_mfma_i32_16x16x64_i8 v[94:97], v[150:153], v[180:183], v[94:97]
	v_mfma_i32_16x16x64_i8 v[90:93], v[160:163], v[180:183], v[90:93]
	v_mfma_i32_16x16x64_i8 v[78:81], v[150:153], v[188:191], v[78:81]
	v_mfma_i32_16x16x64_i8 v[74:77], v[160:163], v[188:191], v[74:77]
	v_mfma_i32_16x16x64_i8 v[70:73], v[150:153], v[196:199], v[70:73]
	v_mfma_i32_16x16x64_i8 v[66:69], v[160:163], v[196:199], v[66:69]
	s_barrier
	s_add_u32 s46, s44, 0x80
	s_addc_u32 s47, s45, 0
	ds_read_b128 v[164:167], v200 offset:49152
	ds_read_b128 v[168:171], v200 offset:50176
	ds_read_b128 v[172:175], v200 offset:51200
	ds_read_b128 v[180:183], v200 offset:52224
	ds_read_b128 v[184:187], v200 offset:53248
	ds_read_b128 v[188:191], v200 offset:54272
	ds_read_b128 v[192:195], v200 offset:55296
	ds_read_b128 v[196:199], v200 offset:56320
	s_add_i32 s29, s29, s48
	v_lshl_add_u64 v[176:177], s[46:47], 0, v[202:203]
	s_mov_b32 m0, s29
	s_add_u32 s46, s46, 0x30000
	global_load_lds_dwordx4 v[176:177], off
	s_addc_u32 s47, s47, 0
	s_add_i32 m0, s29, 0x2000
	s_add_u32 s44, s44, 0x60080
	s_addc_u32 s45, s45, 0
	v_lshl_add_u64 v[176:177], s[46:47], 0, v[202:203]
	global_load_lds_dwordx4 v[176:177], off
	s_add_i32 s29, s76, s48
	v_lshl_add_u64 v[176:177], s[44:45], 0, v[202:203]
	s_add_u32 s44, s44, 0x30000
	s_mov_b32 m0, s29
	s_addc_u32 s45, s45, 0
	global_load_lds_dwordx4 v[176:177], off
	s_add_i32 m0, s29, 0x2000
	v_lshl_add_u64 v[176:177], s[44:45], 0, v[202:203]
	global_load_lds_dwordx4 v[176:177], off
	s_mov_b32 m0, s53
	v_lshl_add_u64 v[176:177], s[10:11], 0, v[158:159]
	s_add_u32 s10, s10, 0x40000
	s_addc_u32 s11, s11, 0
	global_load_lds_dwordx4 v[176:177], off
	s_mov_b32 m0, s54
	v_lshl_add_u64 v[176:177], s[10:11], 0, v[158:159]
	global_load_lds_dwordx4 v[176:177], off
	s_waitcnt vmcnt(8)
	s_waitcnt lgkmcnt(0)
	s_barrier
	v_mfma_i32_16x16x64_i8 v[62:65], v[130:133], v[164:167], v[62:65]
	v_mfma_i32_16x16x64_i8 v[58:61], v[138:141], v[164:167], v[58:61]
	v_mfma_i32_16x16x64_i8 v[54:57], v[130:133], v[172:175], v[54:57]
	v_mfma_i32_16x16x64_i8 v[50:53], v[138:141], v[172:175], v[50:53]
	v_mfma_i32_16x16x64_i8 v[38:41], v[130:133], v[184:187], v[38:41]
	v_mfma_i32_16x16x64_i8 v[34:37], v[138:141], v[184:187], v[34:37]
	v_mfma_i32_16x16x64_i8 v[14:17], v[130:133], v[192:195], v[14:17]
	v_mfma_i32_16x16x64_i8 v[10:13], v[138:141], v[192:195], v[10:13]
	v_mfma_i32_16x16x64_i8 v[62:65], v[134:137], v[168:171], v[62:65]
	v_mfma_i32_16x16x64_i8 v[58:61], v[142:145], v[168:171], v[58:61]
	v_mfma_i32_16x16x64_i8 v[54:57], v[134:137], v[180:183], v[54:57]
	v_mfma_i32_16x16x64_i8 v[50:53], v[142:145], v[180:183], v[50:53]
	v_mfma_i32_16x16x64_i8 v[38:41], v[134:137], v[188:191], v[38:41]
	v_mfma_i32_16x16x64_i8 v[34:37], v[142:145], v[188:191], v[34:37]
	v_mfma_i32_16x16x64_i8 v[14:17], v[134:137], v[196:199], v[14:17]
	v_mfma_i32_16x16x64_i8 v[10:13], v[142:145], v[196:199], v[10:13]
	v_mfma_i32_16x16x64_i8 v[46:49], v[146:149], v[164:167], v[46:49]
	v_mfma_i32_16x16x64_i8 v[42:45], v[154:157], v[164:167], v[42:45]
	v_mfma_i32_16x16x64_i8 v[30:33], v[146:149], v[172:175], v[30:33]
	v_mfma_i32_16x16x64_i8 v[26:29], v[154:157], v[172:175], v[26:29]
	v_mfma_i32_16x16x64_i8 v[22:25], v[146:149], v[184:187], v[22:25]
	v_mfma_i32_16x16x64_i8 v[18:21], v[154:157], v[184:187], v[18:21]
	v_mfma_i32_16x16x64_i8 v[6:9], v[146:149], v[192:195], v[6:9]
	v_mfma_i32_16x16x64_i8 v[2:5], v[154:157], v[192:195], v[2:5]
	v_mfma_i32_16x16x64_i8 v[46:49], v[150:153], v[168:171], v[46:49]
	v_mfma_i32_16x16x64_i8 v[42:45], v[160:163], v[168:171], v[42:45]
	v_mfma_i32_16x16x64_i8 v[30:33], v[150:153], v[180:183], v[30:33]
	v_mfma_i32_16x16x64_i8 v[26:29], v[160:163], v[180:183], v[26:29]
	v_mfma_i32_16x16x64_i8 v[22:25], v[150:153], v[188:191], v[22:25]
	v_mfma_i32_16x16x64_i8 v[18:21], v[160:163], v[188:191], v[18:21]
	v_mfma_i32_16x16x64_i8 v[6:9], v[150:153], v[196:199], v[6:9]
	v_mfma_i32_16x16x64_i8 v[2:5], v[160:163], v[196:199], v[2:5]
	s_barrier
	s_add_u32 s74, s74, 0x100
	s_addc_u32 s75, s75, 0
	s_add_u32 s72, s72, 0x100
	s_addc_u32 s73, s73, 0
	s_cmp_ge_i32 s28, s69
	s_mov_b32 s10, s28
	s_cbranch_scc1 .Lpeel2_exit
